# GU epilogue stores via SGPR base + one 32-bit offset (no per-row mad_i64); tile-index division by 8 as shifts in 3 GEMM tile setups
# speedup vs baseline: 1.0043x; 1.0011x over previous
.LBB0_121:
	s_add_i32 s45, s45, 1
	v_readlane_b32 s6, v254, 5
	v_readlane_b32 s24, v253, 2
	s_mul_i32 s6, s45, s6
	s_mul_hi_u32 s7, s45, s24
	s_add_i32 s7, s7, s6
	s_mul_i32 s6, s45, s24
	v_readlane_b32 s25, v253, 3
	s_add_u32 s24, s6, s98
	v_readlane_b32 s6, v254, 4
	s_addc_u32 s25, s7, s6
	v_readlane_b32 s6, v255, 28
	v_readlane_b32 s7, v255, 29
	s_nop 1
	v_mov_b64_e32 v[0:1], s[6:7]
	v_cmp_ge_i64_e32 vcc, s[24:25], v[0:1]
	v_cmp_lt_i64_e64 s[6:7], s[24:25], v[0:1]
	s_cbranch_vccnz .LBB0_123
	s_ashr_i32 s20, s24, 31
	s_lshr_b32 s20, s20, 29
	s_add_i32 s20, s24, s20
	s_ashr_i32 s21, s20, 3
	s_and_b32 s20, s20, -8
	s_sub_i32 s20, s24, s20
	s_lshr_b32 s22, s20, 31
	v_readlane_b32 s23, v255, 30
	s_or_b32 s22, s23, s22
	s_mul_i32 s20, s22, s20
	s_add_i32 s20, s20, s21
	s_ashr_i32 s21, s20, 31
	v_readlane_b32 s22, v255, 31
	s_xor_b32 s21, s21, s22
	s_abs_i32 s22, s20
	v_readlane_b32 s23, v255, 32
	s_mul_hi_u32 s23, s22, s23
	v_readlane_b32 s26, v255, 33
	s_mul_i32 s24, s23, s26
	s_sub_i32 s22, s22, s24
	s_add_i32 s24, s23, 1
	s_sub_i32 s25, s22, s26
	s_cmp_ge_u32 s22, s26
	s_cselect_b32 s23, s24, s23
	s_cselect_b32 s22, s25, s22
	s_add_i32 s24, s23, 1
	s_cmp_ge_u32 s22, s26
	s_cselect_b32 s22, s24, s23
	s_xor_b32 s22, s22, s21
	s_sub_i32 s21, s22, s21
	s_lshl_b32 s22, s21, 3
	v_readlane_b32 s25, v255, 34
	s_nop 3
	s_mul_i32 s21, s21, s25
	s_sub_i32 s21, s20, s21
	s_lshr_b32 s20, s21, 3
	s_and_b32 s21, s21, 7
	s_add_i32 s22, s21, s22

.LBB0_571:
	s_add_i32 s46, s46, 1
	v_readlane_b32 s4, v254, 5
	v_readlane_b32 s26, v253, 2
	s_mul_i32 s4, s46, s4
	s_mul_hi_u32 s5, s46, s26
	s_add_i32 s5, s5, s4
	s_mul_i32 s4, s46, s26
	v_readlane_b32 s27, v253, 3
	s_add_u32 s26, s4, s98
	v_readlane_b32 s4, v254, 4
	s_addc_u32 s27, s5, s4
	v_mov_b64_e32 v[0:1], 0xb00
	v_cmp_lt_i64_e64 s[4:5], s[26:27], v[0:1]
	v_mov_b64_e32 v[0:1], 0xaff
	v_cmp_gt_i64_e32 vcc, s[26:27], v[0:1]
	s_cbranch_vccnz .LBB0_573
	s_ashr_i32 s22, s26, 31
	s_lshr_b32 s22, s22, 29
	s_add_i32 s22, s26, s22
	s_ashr_i32 s23, s22, 3
	s_and_b32 s22, s22, -8
	s_sub_i32 s22, s26, s22
	s_cmp_lt_i32 s22, 0
	s_movk_i32 s24, 0x161
	s_cselect_b32 s24, s24, 0x160
	s_mul_i32 s22, s22, s24
	s_add_i32 s22, s22, s23
	s_mul_hi_i32 s23, s22, 0x2e8ba2e9
	s_lshr_b32 s24, s23, 31
	s_ashr_i32 s23, s23, 5
	s_add_i32 s23, s23, s24
	s_lshl_b32 s24, s23, 3
	s_mulk_i32 s23, 0xb0
	s_sub_i32 s23, s22, s23
	s_lshr_b32 s22, s23, 3
	s_and_b32 s23, s23, 7
	s_add_i32 s24, s24, s23

.LBB0_577:
	s_mov_b32 s34, 0xbfb8aa3b
	s_mov_b32 s35, 0xbfb8aa3b
	v_lshl_or_b32 v146, s47, 7, v142
	v_lshl_add_u32 v144, s48, 8, v140
	v_mul_u32_u24_e32 v150, 0x1600, v144
	v_lshl_add_u32 v150, v146, 1, v150
	v_pk_mul_f32 v[160:161], v[124:125], s[34:35]
	v_pk_mul_f32 v[162:163], v[126:127], s[34:35]
	v_pk_mul_f32 v[164:165], v[120:121], s[34:35]
	v_pk_mul_f32 v[166:167], v[122:123], s[34:35]
	v_exp_f32_e32 v160, v160
	v_exp_f32_e32 v161, v161
	v_exp_f32_e32 v162, v162
	v_exp_f32_e32 v163, v163
	v_exp_f32_e32 v164, v164
	v_exp_f32_e32 v165, v165
	v_exp_f32_e32 v166, v166
	v_exp_f32_e32 v167, v167
	v_pk_add_f32 v[160:161], v[160:161], 1.0 op_sel_hi:[1,0]
	v_pk_add_f32 v[162:163], v[162:163], 1.0 op_sel_hi:[1,0]
	v_pk_add_f32 v[164:165], v[164:165], 1.0 op_sel_hi:[1,0]
	v_pk_add_f32 v[166:167], v[166:167], 1.0 op_sel_hi:[1,0]
	v_rcp_f32_e32 v160, v160
	v_rcp_f32_e32 v161, v161
	v_rcp_f32_e32 v162, v162
	v_rcp_f32_e32 v163, v163
	v_rcp_f32_e32 v164, v164
	v_rcp_f32_e32 v165, v165
	v_rcp_f32_e32 v166, v166
	v_rcp_f32_e32 v167, v167
	v_pk_mul_f32 v[124:125], v[124:125], v[160:161]
	v_pk_mul_f32 v[126:127], v[126:127], v[162:163]
	v_pk_mul_f32 v[120:121], v[120:121], v[164:165]
	v_pk_mul_f32 v[122:123], v[122:123], v[166:167]
	v_pk_mul_f32 v[116:117], v[124:125], v[116:117]
	v_pk_mul_f32 v[118:119], v[126:127], v[118:119]
	v_pk_mul_f32 v[112:113], v[120:121], v[112:113]
	v_pk_mul_f32 v[114:115], v[122:123], v[114:115]
	v_cvt_pk_bf16_f32 v168, v116, v117
	v_cvt_pk_bf16_f32 v169, v118, v119
	v_cvt_pk_bf16_f32 v170, v112, v113
	v_cvt_pk_bf16_f32 v171, v114, v115
	global_store_dwordx4 v150, v[168:171], s[96:97]
	v_pk_mul_f32 v[160:161], v[108:109], s[34:35]
	v_pk_mul_f32 v[162:163], v[110:111], s[34:35]
	v_pk_mul_f32 v[164:165], v[104:105], s[34:35]
	v_pk_mul_f32 v[166:167], v[106:107], s[34:35]
	v_exp_f32_e32 v160, v160
	v_exp_f32_e32 v161, v161
	v_exp_f32_e32 v162, v162
	v_exp_f32_e32 v163, v163
	v_exp_f32_e32 v164, v164
	v_exp_f32_e32 v165, v165
	v_exp_f32_e32 v166, v166
	v_exp_f32_e32 v167, v167
	v_pk_add_f32 v[160:161], v[160:161], 1.0 op_sel_hi:[1,0]
	v_pk_add_f32 v[162:163], v[162:163], 1.0 op_sel_hi:[1,0]
	v_pk_add_f32 v[164:165], v[164:165], 1.0 op_sel_hi:[1,0]
	v_pk_add_f32 v[166:167], v[166:167], 1.0 op_sel_hi:[1,0]
	v_rcp_f32_e32 v160, v160
	v_rcp_f32_e32 v161, v161
	v_rcp_f32_e32 v162, v162
	v_rcp_f32_e32 v163, v163
	v_rcp_f32_e32 v164, v164
	v_rcp_f32_e32 v165, v165
	v_rcp_f32_e32 v166, v166
	v_rcp_f32_e32 v167, v167
	v_pk_mul_f32 v[108:109], v[108:109], v[160:161]
	v_pk_mul_f32 v[110:111], v[110:111], v[162:163]
	v_pk_mul_f32 v[104:105], v[104:105], v[164:165]
	v_pk_mul_f32 v[106:107], v[106:107], v[166:167]
	v_pk_mul_f32 v[100:101], v[108:109], v[100:101]
	v_pk_mul_f32 v[102:103], v[110:111], v[102:103]
	v_pk_mul_f32 v[96:97], v[104:105], v[96:97]
	v_pk_mul_f32 v[98:99], v[106:107], v[98:99]
	v_cvt_pk_bf16_f32 v172, v100, v101
	v_cvt_pk_bf16_f32 v173, v102, v103
	v_cvt_pk_bf16_f32 v174, v96, v97
	v_cvt_pk_bf16_f32 v175, v98, v99
	s_add_u32 s30, s96, 0x16000
	s_addc_u32 s31, s97, 0
	global_store_dwordx4 v150, v[172:175], s[30:31]
	v_pk_mul_f32 v[160:161], v[92:93], s[34:35]
	v_pk_mul_f32 v[162:163], v[94:95], s[34:35]
	v_pk_mul_f32 v[164:165], v[88:89], s[34:35]
	v_pk_mul_f32 v[166:167], v[90:91], s[34:35]
	v_exp_f32_e32 v160, v160
	v_exp_f32_e32 v161, v161
	v_exp_f32_e32 v162, v162
	v_exp_f32_e32 v163, v163
	v_exp_f32_e32 v164, v164
	v_exp_f32_e32 v165, v165
	v_exp_f32_e32 v166, v166
	v_exp_f32_e32 v167, v167
	v_pk_add_f32 v[160:161], v[160:161], 1.0 op_sel_hi:[1,0]
	v_pk_add_f32 v[162:163], v[162:163], 1.0 op_sel_hi:[1,0]
	v_pk_add_f32 v[164:165], v[164:165], 1.0 op_sel_hi:[1,0]
	v_pk_add_f32 v[166:167], v[166:167], 1.0 op_sel_hi:[1,0]
	v_rcp_f32_e32 v160, v160
	v_rcp_f32_e32 v161, v161
	v_rcp_f32_e32 v162, v162
	v_rcp_f32_e32 v163, v163
	v_rcp_f32_e32 v164, v164
	v_rcp_f32_e32 v165, v165
	v_rcp_f32_e32 v166, v166
	v_rcp_f32_e32 v167, v167
	v_pk_mul_f32 v[92:93], v[92:93], v[160:161]
	v_pk_mul_f32 v[94:95], v[94:95], v[162:163]
	v_pk_mul_f32 v[88:89], v[88:89], v[164:165]
	v_pk_mul_f32 v[90:91], v[90:91], v[166:167]
	v_pk_mul_f32 v[84:85], v[92:93], v[84:85]
	v_pk_mul_f32 v[86:87], v[94:95], v[86:87]
	v_pk_mul_f32 v[80:81], v[88:89], v[80:81]
	v_pk_mul_f32 v[82:83], v[90:91], v[82:83]
	v_cvt_pk_bf16_f32 v168, v84, v85
	v_cvt_pk_bf16_f32 v169, v86, v87
	v_cvt_pk_bf16_f32 v170, v80, v81
	v_cvt_pk_bf16_f32 v171, v82, v83
	s_add_u32 s30, s96, 0x2c000
	s_addc_u32 s31, s97, 0
	global_store_dwordx4 v150, v[168:171], s[30:31]
	v_pk_mul_f32 v[160:161], v[76:77], s[34:35]
	v_pk_mul_f32 v[162:163], v[78:79], s[34:35]
	v_pk_mul_f32 v[164:165], v[72:73], s[34:35]
	v_pk_mul_f32 v[166:167], v[74:75], s[34:35]
	v_exp_f32_e32 v160, v160
	v_exp_f32_e32 v161, v161
	v_exp_f32_e32 v162, v162
	v_exp_f32_e32 v163, v163
	v_exp_f32_e32 v164, v164
	v_exp_f32_e32 v165, v165
	v_exp_f32_e32 v166, v166
	v_exp_f32_e32 v167, v167
	v_pk_add_f32 v[160:161], v[160:161], 1.0 op_sel_hi:[1,0]
	v_pk_add_f32 v[162:163], v[162:163], 1.0 op_sel_hi:[1,0]
	v_pk_add_f32 v[164:165], v[164:165], 1.0 op_sel_hi:[1,0]
	v_pk_add_f32 v[166:167], v[166:167], 1.0 op_sel_hi:[1,0]
	v_rcp_f32_e32 v160, v160
	v_rcp_f32_e32 v161, v161
	v_rcp_f32_e32 v162, v162
	v_rcp_f32_e32 v163, v163
	v_rcp_f32_e32 v164, v164
	v_rcp_f32_e32 v165, v165
	v_rcp_f32_e32 v166, v166
	v_rcp_f32_e32 v167, v167
	v_pk_mul_f32 v[76:77], v[76:77], v[160:161]
	v_pk_mul_f32 v[78:79], v[78:79], v[162:163]
	v_pk_mul_f32 v[72:73], v[72:73], v[164:165]
	v_pk_mul_f32 v[74:75], v[74:75], v[166:167]
	v_pk_mul_f32 v[68:69], v[76:77], v[68:69]
	v_pk_mul_f32 v[70:71], v[78:79], v[70:71]
	v_pk_mul_f32 v[64:65], v[72:73], v[64:65]
	v_pk_mul_f32 v[66:67], v[74:75], v[66:67]
	v_cvt_pk_bf16_f32 v172, v68, v69
	v_cvt_pk_bf16_f32 v173, v70, v71
	v_cvt_pk_bf16_f32 v174, v64, v65
	v_cvt_pk_bf16_f32 v175, v66, v67
	s_add_u32 s30, s96, 0x42000
	s_addc_u32 s31, s97, 0
	global_store_dwordx4 v150, v[172:175], s[30:31]
	v_pk_mul_f32 v[160:161], v[60:61], s[34:35]
	v_pk_mul_f32 v[162:163], v[62:63], s[34:35]
	v_pk_mul_f32 v[164:165], v[56:57], s[34:35]
	v_pk_mul_f32 v[166:167], v[58:59], s[34:35]
	v_exp_f32_e32 v160, v160
	v_exp_f32_e32 v161, v161
	v_exp_f32_e32 v162, v162
	v_exp_f32_e32 v163, v163
	v_exp_f32_e32 v164, v164
	v_exp_f32_e32 v165, v165
	v_exp_f32_e32 v166, v166
	v_exp_f32_e32 v167, v167
	v_pk_add_f32 v[160:161], v[160:161], 1.0 op_sel_hi:[1,0]
	v_pk_add_f32 v[162:163], v[162:163], 1.0 op_sel_hi:[1,0]
	v_pk_add_f32 v[164:165], v[164:165], 1.0 op_sel_hi:[1,0]
	v_pk_add_f32 v[166:167], v[166:167], 1.0 op_sel_hi:[1,0]
	v_rcp_f32_e32 v160, v160
	v_rcp_f32_e32 v161, v161
	v_rcp_f32_e32 v162, v162
	v_rcp_f32_e32 v163, v163
	v_rcp_f32_e32 v164, v164
	v_rcp_f32_e32 v165, v165
	v_rcp_f32_e32 v166, v166
	v_rcp_f32_e32 v167, v167
	v_pk_mul_f32 v[60:61], v[60:61], v[160:161]
	v_pk_mul_f32 v[62:63], v[62:63], v[162:163]
	v_pk_mul_f32 v[56:57], v[56:57], v[164:165]
	v_pk_mul_f32 v[58:59], v[58:59], v[166:167]
	v_pk_mul_f32 v[52:53], v[60:61], v[52:53]
	v_pk_mul_f32 v[54:55], v[62:63], v[54:55]
	v_pk_mul_f32 v[48:49], v[56:57], v[48:49]
	v_pk_mul_f32 v[50:51], v[58:59], v[50:51]
	v_cvt_pk_bf16_f32 v168, v52, v53
	v_cvt_pk_bf16_f32 v169, v54, v55
	v_cvt_pk_bf16_f32 v170, v48, v49
	v_cvt_pk_bf16_f32 v171, v50, v51
	s_add_u32 s30, s96, 0xb0000
	s_addc_u32 s31, s97, 0
	global_store_dwordx4 v150, v[168:171], s[30:31]
	v_pk_mul_f32 v[160:161], v[44:45], s[34:35]
	v_pk_mul_f32 v[162:163], v[46:47], s[34:35]
	v_pk_mul_f32 v[164:165], v[40:41], s[34:35]
	v_pk_mul_f32 v[166:167], v[42:43], s[34:35]
	v_exp_f32_e32 v160, v160
	v_exp_f32_e32 v161, v161
	v_exp_f32_e32 v162, v162
	v_exp_f32_e32 v163, v163
	v_exp_f32_e32 v164, v164
	v_exp_f32_e32 v165, v165
	v_exp_f32_e32 v166, v166
	v_exp_f32_e32 v167, v167
	v_pk_add_f32 v[160:161], v[160:161], 1.0 op_sel_hi:[1,0]
	v_pk_add_f32 v[162:163], v[162:163], 1.0 op_sel_hi:[1,0]
	v_pk_add_f32 v[164:165], v[164:165], 1.0 op_sel_hi:[1,0]
	v_pk_add_f32 v[166:167], v[166:167], 1.0 op_sel_hi:[1,0]
	v_rcp_f32_e32 v160, v160
	v_rcp_f32_e32 v161, v161
	v_rcp_f32_e32 v162, v162
	v_rcp_f32_e32 v163, v163
	v_rcp_f32_e32 v164, v164
	v_rcp_f32_e32 v165, v165
	v_rcp_f32_e32 v166, v166
	v_rcp_f32_e32 v167, v167
	v_pk_mul_f32 v[44:45], v[44:45], v[160:161]
	v_pk_mul_f32 v[46:47], v[46:47], v[162:163]
	v_pk_mul_f32 v[40:41], v[40:41], v[164:165]
	v_pk_mul_f32 v[42:43], v[42:43], v[166:167]
	v_pk_mul_f32 v[36:37], v[44:45], v[36:37]
	v_pk_mul_f32 v[38:39], v[46:47], v[38:39]
	v_pk_mul_f32 v[32:33], v[40:41], v[32:33]
	v_pk_mul_f32 v[34:35], v[42:43], v[34:35]
	v_cvt_pk_bf16_f32 v172, v36, v37
	v_cvt_pk_bf16_f32 v173, v38, v39
	v_cvt_pk_bf16_f32 v174, v32, v33
	v_cvt_pk_bf16_f32 v175, v34, v35
	s_add_u32 s30, s96, 0xc6000
	s_addc_u32 s31, s97, 0
	global_store_dwordx4 v150, v[172:175], s[30:31]
	v_pk_mul_f32 v[160:161], v[28:29], s[34:35]
	v_pk_mul_f32 v[162:163], v[30:31], s[34:35]
	v_pk_mul_f32 v[164:165], v[24:25], s[34:35]
	v_pk_mul_f32 v[166:167], v[26:27], s[34:35]
	v_exp_f32_e32 v160, v160
	v_exp_f32_e32 v161, v161
	v_exp_f32_e32 v162, v162
	v_exp_f32_e32 v163, v163
	v_exp_f32_e32 v164, v164
	v_exp_f32_e32 v165, v165
	v_exp_f32_e32 v166, v166
	v_exp_f32_e32 v167, v167
	v_pk_add_f32 v[160:161], v[160:161], 1.0 op_sel_hi:[1,0]
	v_pk_add_f32 v[162:163], v[162:163], 1.0 op_sel_hi:[1,0]
	v_pk_add_f32 v[164:165], v[164:165], 1.0 op_sel_hi:[1,0]
	v_pk_add_f32 v[166:167], v[166:167], 1.0 op_sel_hi:[1,0]
	v_rcp_f32_e32 v160, v160
	v_rcp_f32_e32 v161, v161
	v_rcp_f32_e32 v162, v162
	v_rcp_f32_e32 v163, v163
	v_rcp_f32_e32 v164, v164
	v_rcp_f32_e32 v165, v165
	v_rcp_f32_e32 v166, v166
	v_rcp_f32_e32 v167, v167
	v_pk_mul_f32 v[28:29], v[28:29], v[160:161]
	v_pk_mul_f32 v[30:31], v[30:31], v[162:163]
	v_pk_mul_f32 v[24:25], v[24:25], v[164:165]
	v_pk_mul_f32 v[26:27], v[26:27], v[166:167]
	v_pk_mul_f32 v[20:21], v[28:29], v[20:21]
	v_pk_mul_f32 v[22:23], v[30:31], v[22:23]
	v_pk_mul_f32 v[16:17], v[24:25], v[16:17]
	v_pk_mul_f32 v[18:19], v[26:27], v[18:19]
	v_cvt_pk_bf16_f32 v168, v20, v21
	v_cvt_pk_bf16_f32 v169, v22, v23
	v_cvt_pk_bf16_f32 v170, v16, v17
	v_cvt_pk_bf16_f32 v171, v18, v19
	s_add_u32 s30, s96, 0xdc000
	s_addc_u32 s31, s97, 0
	global_store_dwordx4 v150, v[168:171], s[30:31]
	v_pk_mul_f32 v[160:161], v[12:13], s[34:35]
	v_pk_mul_f32 v[162:163], v[14:15], s[34:35]
	v_pk_mul_f32 v[164:165], v[8:9], s[34:35]
	v_pk_mul_f32 v[166:167], v[10:11], s[34:35]
	v_exp_f32_e32 v160, v160
	v_exp_f32_e32 v161, v161
	v_exp_f32_e32 v162, v162
	v_exp_f32_e32 v163, v163
	v_exp_f32_e32 v164, v164
	v_exp_f32_e32 v165, v165
	v_exp_f32_e32 v166, v166
	v_exp_f32_e32 v167, v167
	v_pk_add_f32 v[160:161], v[160:161], 1.0 op_sel_hi:[1,0]
	v_pk_add_f32 v[162:163], v[162:163], 1.0 op_sel_hi:[1,0]
	v_pk_add_f32 v[164:165], v[164:165], 1.0 op_sel_hi:[1,0]
	v_pk_add_f32 v[166:167], v[166:167], 1.0 op_sel_hi:[1,0]
	v_rcp_f32_e32 v160, v160
	v_rcp_f32_e32 v161, v161
	v_rcp_f32_e32 v162, v162
	v_rcp_f32_e32 v163, v163
	v_rcp_f32_e32 v164, v164
	v_rcp_f32_e32 v165, v165
	v_rcp_f32_e32 v166, v166
	v_rcp_f32_e32 v167, v167
	v_pk_mul_f32 v[12:13], v[12:13], v[160:161]
	v_pk_mul_f32 v[14:15], v[14:15], v[162:163]
	v_pk_mul_f32 v[8:9], v[8:9], v[164:165]
	v_pk_mul_f32 v[10:11], v[10:11], v[166:167]
	v_pk_mul_f32 v[4:5], v[12:13], v[4:5]
	v_pk_mul_f32 v[6:7], v[14:15], v[6:7]
	v_pk_mul_f32 v[0:1], v[8:9], v[0:1]
	v_pk_mul_f32 v[2:3], v[10:11], v[2:3]
	v_cvt_pk_bf16_f32 v172, v4, v5
	v_cvt_pk_bf16_f32 v173, v6, v7
	v_cvt_pk_bf16_f32 v174, v0, v1
	v_cvt_pk_bf16_f32 v175, v2, v3
	s_add_u32 s30, s96, 0xf2000
	s_addc_u32 s31, s97, 0
	global_store_dwordx4 v150, v[172:175], s[30:31]
	s_andn2_b64 vcc, exec, s[4:5]
	s_mov_b64 s[4:5], -1
	s_cbranch_vccnz .LBB0_570
	s_andn2_b64 vcc, exec, s[12:13]
	s_cbranch_vccnz .LBB0_569
	s_barrier
	s_branch .LBB0_569

.LBB0_662:
	s_ashr_i32 s10, s46, 3
	s_add_i32 s10, s48, s10
	s_ashr_i32 s11, s10, 31
	s_lshr_b32 s11, s11, 27
	s_add_i32 s11, s10, s11
	s_ashr_i32 s46, s11, 5
	s_lshl_b32 s46, s46, 3
	s_andn2_b32 s11, s11, 31
	s_sub_i32 s10, s10, s11
	s_lshr_b32 s76, s10, 3
	s_and_b32 s10, s10, 7
	s_add_i32 s77, s46, s10
